# v10 + W_out phase: workgroups with id bit 3 set run their half tile first and the full tile second, so half of the chip is in a K-loop while the other half streams its HBM-bound epilogue
# speedup vs baseline: 1.0110x; 1.0075x over previous
.LBB0_947:
	s_or_b64 exec, exec, s[6:7]
	v_mov_b32_e32 v12, v234
	s_waitcnt lgkmcnt(0)
	s_barrier
	s_and_b64 vcc, exec, s[4:5]
	v_readfirstlane_b32 s10, v12
	s_cbranch_vccnz .LBB0_949
	s_mov_b32 s100, s2
	s_bitcmp1_b32 s2, 3
	s_cbranch_scc0 .Lwo_y_first
	s_cmp_eq_u32 s56, 0x100
	s_cbranch_scc0 .Lwo_y_first
	s_lshr_b32 s100, s2, 1
	s_add_u32 s100, s100, 0x100
.Lwo_y_first:
	s_mul_hi_i32 s101, s100, 0x2aaaaaab
	s_lshr_b32 s6, s101, 31
	s_ashr_i32 s7, s101, 6
	s_add_i32 s8, s7, s6
	s_mul_i32 s6, s8, 0xfffffe80
	s_add_i32 s6, s6, s100
	s_ashr_i32 s7, s6, 31
	s_lshr_b32 s7, s7, 29
	s_add_i32 s7, s6, s7
	s_ashr_i32 s9, s7, 3
	s_and_b32 s7, s7, -8
	s_sub_i32 s6, s6, s7
	s_cmp_lt_i32 s6, 0
	s_cselect_b32 s7, 49, 48
	s_mul_i32 s6, s7, s6
	s_add_i32 s6, s6, s9
	s_ashr_i32 s7, s6, 31
	s_lshr_b32 s7, s7, 27
	s_add_i32 s7, s6, s7
	s_ashr_i32 s9, s7, 5
	s_lshl_b32 s9, s9, 3
	s_sub_i32 s11, 0x60, s9
	s_min_i32 s11, s11, 8
	s_abs_i32 s12, s11
	v_cvt_f32_u32_e32 v0, s12
	s_sub_i32 s14, 0, s12
	s_andn2_b32 s7, s7, 31
	s_sub_i32 s6, s6, s7
	v_rcp_iflag_f32_e32 v0, v0
	s_abs_i32 s7, s6
	s_xor_b32 s13, s6, s11
	s_ashr_i32 s13, s13, 31
	v_mul_f32_e32 v0, 0x4f7ffffe, v0
	v_cvt_u32_f32_e32 v0, v0
	s_nop 0
	v_readfirstlane_b32 s15, v0
	s_mul_i32 s14, s14, s15
	s_mul_hi_u32 s14, s15, s14
	s_add_i32 s15, s15, s14
	s_mul_hi_u32 s14, s7, s15
	s_mul_i32 s15, s14, s12
	s_sub_i32 s7, s7, s15
	s_add_i32 s16, s14, 1
	s_sub_i32 s15, s7, s12
	s_cmp_ge_u32 s7, s12
	s_cselect_b32 s14, s16, s14
	s_cselect_b32 s7, s15, s7
	s_add_i32 s15, s14, 1
	s_cmp_ge_u32 s7, s12
	s_cselect_b32 s7, s15, s14
	s_xor_b32 s7, s7, s13
	s_sub_i32 s66, s7, s13
	s_mul_i32 s7, s66, s11
	s_sub_i32 s6, s6, s7
	s_add_i32 s6, s6, s9
	s_ashr_i32 s9, s8, 31
	s_lshl_b64 s[8:9], s[8:9], 11
	s_and_b64 vcc, exec, s[4:5]
	s_cbranch_vccz .LBB0_950
	s_branch .LBB0_1045

.LBB0_950:
	v_ashrrev_i32_e32 v1, 31, v12
	v_lshrrev_b32_e32 v1, 26, v1
	v_add_u32_e32 v1, v12, v1
	v_ashrrev_i32_e32 v13, 6, v1
	v_bfe_i32 v1, v12, 27, 1
	v_lshlrev_b32_e32 v0, 4, v12
	v_lshrrev_b32_e32 v1, 22, v1
	v_add_u32_e32 v1, v0, v1
	v_and_b32_e32 v1, 0xfffffc00, v1
	v_sub_u32_e32 v1, v0, v1
	v_lshrrev_b32_e32 v2, 4, v1
	v_bitop3_b32 v1, v2, v1, 32 bitop3:0x6c
	v_ashrrev_i32_e32 v3, 31, v1
	v_lshrrev_b32_e32 v3, 26, v3
	v_add_u32_e32 v3, v1, v3
	v_lshlrev_b32_e32 v2, 3, v13
	v_ashrrev_i32_e32 v14, 6, v3
	v_and_b32_e32 v3, 0xc0, v3
	v_and_b32_e32 v2, -16, v2
	v_sub_u32_e32 v1, v1, v3
	v_mov_b32_e32 v3, 1
	s_mov_b64 s[4:5], 0x1600000
	v_add_u32_e32 v2, v14, v2
	v_ashrrev_i16_sdwa v1, v3, sext(v1) dst_sel:DWORD dst_unused:UNUSED_PAD src0_sel:DWORD src1_sel:BYTE_0
	v_lshl_add_u64 v[188:189], v[160:161], 0, s[4:5]
	v_lshlrev_b32_e32 v4, 5, v13
	v_bfe_i32 v15, v1, 0, 16
	v_lshlrev_b32_e32 v1, 1, v2
	v_lshrrev_b32_e32 v5, 2, v2
	v_and_b32_e32 v6, 3, v14
	s_mov_b32 s5, 0x1fffe0
	v_and_b32_e32 v4, 32, v4
	v_and_b32_e32 v1, 24, v1
	v_and_b32_e32 v5, 4, v5
	v_and_or_b32 v6, v2, s5, v6
	v_or3_b32 v1, v6, v5, v1
	v_add_lshl_u32 v4, v4, v15, 1
	v_add_u32_e32 v0, 0x2000, v0
	v_lshl_add_u32 v192, v1, 11, v4
	v_ashrrev_i32_e32 v1, 31, v0
	v_lshrrev_b32_e32 v1, 22, v1
	v_add_u32_e32 v1, v0, v1
	v_ashrrev_i32_e32 v16, 10, v1
	v_mul_i32_i24_e32 v1, 0x400, v16
	v_sub_u32_e32 v0, v0, v1
	v_lshrrev_b32_e32 v1, 4, v0
	v_bitop3_b32 v0, v1, v0, 32 bitop3:0x6c
	v_lshl_add_u32 v190, v2, 11, v4
	v_ashrrev_i32_e32 v2, 31, v0
	v_lshrrev_b32_e32 v2, 26, v2
	v_add_u32_e32 v2, v0, v2
	v_lshlrev_b32_e32 v1, 3, v16
	v_ashrrev_i32_e32 v17, 6, v2
	v_and_b32_e32 v2, 0xc0, v2
	v_and_b32_e32 v1, -16, v1
	v_sub_u32_e32 v0, v0, v2
	v_add_u32_e32 v1, v17, v1
	v_ashrrev_i16_sdwa v0, v3, sext(v0) dst_sel:DWORD dst_unused:UNUSED_PAD src0_sel:DWORD src1_sel:BYTE_0
	v_lshlrev_b32_e32 v4, 5, v16
	s_waitcnt vmcnt(3)
	v_bfe_i32 v18, v0, 0, 16
	v_lshlrev_b32_e32 v0, 1, v1
	v_lshrrev_b32_e32 v2, 2, v1
	v_and_b32_e32 v3, 3, v17
	v_and_b32_e32 v4, 32, v4
	v_and_b32_e32 v0, 24, v0
	v_and_b32_e32 v2, 4, v2
	v_and_or_b32 v3, v1, s5, v3
	s_ashr_i32 s7, s6, 31
	v_or3_b32 v0, v3, v2, v0
	v_add_lshl_u32 v2, v4, v18, 1
	s_lshl_b64 s[12:13], s[6:7], 19
	s_bitcmp1_b32 s2, 3
	s_cbranch_scc0 .Lwo_y_a0
	s_cmp_eq_u32 s56, 0x100
	s_cbranch_scc0 .Lwo_y_a0
	s_and_b32 s100, s2, 1
	s_lshl_b32 s100, s100, 18
	s_or_b32 s12, s12, s100
.Lwo_y_a0:
	s_ashr_i32 s67, s66, 31
	s_ashr_i32 s4, s10, 6
	v_lshl_add_u32 v194, v1, 11, v2
	v_lshl_add_u32 v196, v0, 11, v2
	v_lshl_add_u64 v[2:3], v[186:187], 0, s[12:13]
	s_lshl_b64 s[12:13], s[66:67], 19
	s_lshl_b32 s68, s4, 10
	v_lshl_add_u64 v[0:1], v[188:189], 0, s[12:13]
	v_mov_b32_e32 v199, 0
	v_lshl_add_u64 v[0:1], v[0:1], 0, s[8:9]
	s_add_i32 s69, s68, 0
	v_mov_b32_e32 v193, v199
	s_add_i32 m0, s69, 0x10000
	v_lshl_add_u64 v[4:5], v[0:1], 0, v[192:193]
	v_mov_b32_e32 v197, v199
	s_mov_b64 s[16:17], 0x40000
	global_load_lds_dwordx4 v[4:5], off
	v_lshl_add_u64 v[6:7], v[0:1], 0, v[196:197]
	s_add_i32 m0, s69, 0x12000
	v_lshl_add_u64 v[8:9], v[0:1], 0, s[16:17]
	global_load_lds_dwordx4 v[6:7], off
	s_add_i32 m0, s69, 0x14000
	v_lshl_add_u64 v[10:11], v[8:9], 0, v[192:193]
	global_load_lds_dwordx4 v[10:11], off
	v_lshl_add_u64 v[8:9], v[8:9], 0, v[196:197]
	s_add_i32 m0, s69, 0x16000
	v_lshl_add_u64 v[2:3], v[2:3], 0, s[8:9]
	v_mov_b32_e32 v191, v199
	global_load_lds_dwordx4 v[8:9], off
	v_lshl_add_u64 v[8:9], v[2:3], 0, v[190:191]
	s_mov_b32 m0, s69
	v_mov_b32_e32 v195, v199
	s_add_i32 s70, s69, 0x2000
	global_load_lds_dwordx4 v[8:9], off
	v_lshl_add_u64 v[10:11], v[2:3], 0, v[194:195]
	s_mov_b32 m0, s70
	v_lshl_add_u64 v[20:21], v[2:3], 0, s[16:17]
	s_add_i32 s71, s69, 0x4000
	global_load_lds_dwordx4 v[10:11], off
	s_waitcnt vmcnt(6)
	v_lshl_add_u64 v[22:23], v[20:21], 0, v[190:191]
	s_mov_b32 m0, s71
	s_add_i32 s72, s69, 0x6000
	global_load_lds_dwordx4 v[22:23], off
	v_lshl_add_u64 v[20:21], v[20:21], 0, v[194:195]
	s_mov_b32 m0, s72
	s_ashr_i32 s5, s10, 8
	global_load_lds_dwordx4 v[20:21], off
	s_load_dwordx4 s[12:15], s[0:1], 0x0
	s_load_dwordx2 s[18:19], s[0:1], 0xd0
	s_load_dwordx2 s[20:21], s[0:1], 0x100
	s_cmp_eq_u32 s5, 1
	s_cselect_b64 s[22:23], -1, 0
	s_cmp_lg_u32 s5, 1
	s_mov_b32 s25, 0
	s_cbranch_scc1 .LBB0_952
	s_barrier

.LBB0_955:
	s_add_i32 s84, s84, 1
	s_mul_i32 s4, s84, s78
	s_mul_hi_u32 s5, s84, s79
	s_add_i32 s5, s5, s4
	s_mul_i32 s4, s84, s79
	s_add_u32 s8, s4, s2
	s_addc_u32 s9, s5, s80
	s_cmp_eq_u32 s84, 1
	s_cbranch_scc0 .Lwo_half_enum_skip
	s_cmp_eq_u32 s79, 0x100
	s_cbranch_scc0 .Lwo_half_enum_skip
	s_lshr_b32 s8, s2, 1
	s_add_u32 s8, s8, 0x100
	s_mov_b32 s9, 0
	s_bitcmp1_b32 s2, 3
	s_cselect_b32 s8, s2, s8

.LBB0_957:
	s_ashr_i32 s65, s64, 31
	s_lshl_b64 s[8:9], s[64:65], 19
	s_cmp_eq_u32 s84, 1
	s_cbranch_scc0 .Lwo_half_a_skip
	s_cmp_eq_u32 s79, 0x100
	s_cbranch_scc0 .Lwo_half_a_skip
	s_bitcmp1_b32 s2, 3
	s_cbranch_scc1 .Lwo_half_a_skip
	s_and_b32 s10, s2, 1
	s_lshl_b32 s10, s10, 18
	s_or_b32 s8, s8, s10

.LBB0_958:
	v_add_u32_e32 v164, s82, v237
	ds_read_b128 v[56:59], v239
	ds_read_b128 v[60:63], v239 offset:1024
	ds_read_b128 v[144:147], v239 offset:2048
	ds_read_b128 v[148:151], v239 offset:3072
	ds_read_b128 v[152:155], v164
	ds_read_b128 v[156:159], v164 offset:1024
	ds_read_b128 v[160:163], v164 offset:2048
	ds_read_b128 v[164:167], v164 offset:3072
	s_cmp_eq_u32 s7, 12
	v_lshl_add_u64 v[168:169], v[44:45], 0, s[36:37]
	s_cselect_b64 vcc, -1, 0
	v_cndmask_b32_e32 v241, v169, v41, vcc
	v_cndmask_b32_e32 v240, v168, v40, vcc
	v_cndmask_b32_e32 v243, v47, v43, vcc
	v_cndmask_b32_e32 v242, v46, v42, vcc
	v_lshl_add_u64 v[244:245], v[44:45], 0, v[208:209]
	s_add_i32 m0, s69, 0xc000
	ds_read_b128 v[168:171], v238
	ds_read_b128 v[172:175], v238 offset:1024
	ds_read_b128 v[176:179], v238 offset:2048
	ds_read_b128 v[180:183], v238 offset:3072
	ds_read_b128 v[218:221], v238 offset:4096
	ds_read_b128 v[222:225], v238 offset:5120
	ds_read_b128 v[226:229], v238 offset:6144
	ds_read_b128 v[230:233], v238 offset:7168
	global_load_lds_dwordx4 v[244:245], off
	v_lshl_add_u64 v[244:245], v[44:45], 0, v[210:211]
	s_add_i32 m0, s69, 0xe000
	s_nop 0
	global_load_lds_dwordx4 v[244:245], off
	s_waitcnt vmcnt(8)
	s_waitcnt lgkmcnt(0)
	s_barrier
	s_setprio 1
	s_waitcnt lgkmcnt(0)
	v_mfma_f32_16x16x32_bf16 v[140:143], v[56:59], v[168:171], v[140:143]
	v_mfma_f32_16x16x32_bf16 v[136:139], v[144:147], v[168:171], v[136:139]
	v_mfma_f32_16x16x32_bf16 v[124:127], v[56:59], v[176:179], v[124:127]
	v_mfma_f32_16x16x32_bf16 v[120:123], v[144:147], v[176:179], v[120:123]
	v_mfma_f32_16x16x32_bf16 v[108:111], v[56:59], v[218:221], v[108:111]
	v_mfma_f32_16x16x32_bf16 v[104:107], v[144:147], v[218:221], v[104:107]
	v_mfma_f32_16x16x32_bf16 v[92:95], v[56:59], v[226:229], v[92:95]
	v_mfma_f32_16x16x32_bf16 v[88:91], v[144:147], v[226:229], v[88:91]
	v_mfma_f32_16x16x32_bf16 v[140:143], v[60:63], v[172:175], v[140:143]
	v_mfma_f32_16x16x32_bf16 v[136:139], v[148:151], v[172:175], v[136:139]
	v_mfma_f32_16x16x32_bf16 v[124:127], v[60:63], v[180:183], v[124:127]
	v_mfma_f32_16x16x32_bf16 v[120:123], v[148:151], v[180:183], v[120:123]
	v_mfma_f32_16x16x32_bf16 v[108:111], v[60:63], v[222:225], v[108:111]
	v_mfma_f32_16x16x32_bf16 v[104:107], v[148:151], v[222:225], v[104:107]
	v_mfma_f32_16x16x32_bf16 v[92:95], v[60:63], v[230:233], v[92:95]
	v_mfma_f32_16x16x32_bf16 v[88:91], v[148:151], v[230:233], v[88:91]
	s_setprio 0
	s_setprio 1
	v_mfma_f32_16x16x32_bf16 v[132:135], v[152:155], v[168:171], v[132:135]
	v_mfma_f32_16x16x32_bf16 v[128:131], v[160:163], v[168:171], v[128:131]
	v_mfma_f32_16x16x32_bf16 v[116:119], v[152:155], v[176:179], v[116:119]
	v_mfma_f32_16x16x32_bf16 v[112:115], v[160:163], v[176:179], v[112:115]
	v_mfma_f32_16x16x32_bf16 v[100:103], v[152:155], v[218:221], v[100:103]
	v_mfma_f32_16x16x32_bf16 v[96:99], v[160:163], v[218:221], v[96:99]
	v_mfma_f32_16x16x32_bf16 v[84:87], v[152:155], v[226:229], v[84:87]
	v_mfma_f32_16x16x32_bf16 v[80:83], v[160:163], v[226:229], v[80:83]
	v_mfma_f32_16x16x32_bf16 v[132:135], v[156:159], v[172:175], v[132:135]
	v_mfma_f32_16x16x32_bf16 v[128:131], v[164:167], v[172:175], v[128:131]
	v_mfma_f32_16x16x32_bf16 v[116:119], v[156:159], v[180:183], v[116:119]
	v_mfma_f32_16x16x32_bf16 v[112:115], v[164:167], v[180:183], v[112:115]
	v_mfma_f32_16x16x32_bf16 v[100:103], v[156:159], v[222:225], v[100:103]
	v_mfma_f32_16x16x32_bf16 v[96:99], v[164:167], v[222:225], v[96:99]
	v_mfma_f32_16x16x32_bf16 v[84:87], v[156:159], v[230:233], v[84:87]
	v_mfma_f32_16x16x32_bf16 v[80:83], v[164:167], v[230:233], v[80:83]
	s_setprio 0
	s_barrier
	s_add_i32 s8, s81, s68
	v_lshl_add_u64 v[244:245], v[242:243], 0, v[192:193]
	s_mov_b32 m0, s8
	ds_read_b128 v[168:171], v238 offset:16384
	ds_read_b128 v[172:175], v238 offset:17408
	ds_read_b128 v[176:179], v238 offset:18432
	ds_read_b128 v[180:183], v238 offset:19456
	ds_read_b128 v[218:221], v238 offset:20480
	ds_read_b128 v[222:225], v238 offset:21504
	ds_read_b128 v[226:229], v238 offset:22528
	ds_read_b128 v[230:233], v238 offset:23552
	global_load_lds_dwordx4 v[244:245], off
	v_lshl_add_u64 v[246:247], v[242:243], 0, v[196:197]
	s_add_i32 m0, s8, 0x2000
	v_lshl_add_u64 v[248:249], v[242:243], 0, s[16:17]
	s_add_i32 s8, s82, s68
	global_load_lds_dwordx4 v[246:247], off
	v_lshl_add_u64 v[250:251], v[248:249], 0, v[192:193]
	s_mov_b32 m0, s8
	v_lshl_add_u64 v[248:249], v[248:249], 0, v[196:197]
	global_load_lds_dwordx4 v[250:251], off
	s_add_i32 m0, s8, 0x2000
	v_lshl_add_u64 v[250:251], v[240:241], 0, v[194:195]
	global_load_lds_dwordx4 v[248:249], off
	v_lshl_add_u64 v[248:249], v[240:241], 0, v[190:191]
	s_waitcnt vmcnt(6)
	s_waitcnt lgkmcnt(0)
	s_barrier
	s_setprio 1
	s_waitcnt lgkmcnt(0)
	s_bfe_u32 s101, s2, 0x10003
	s_sub_i32 s101, 2, s101
	s_cmp_eq_u32 s84, s101
	s_cbranch_scc0 .Lwo_half_full_a
	s_cmp_eq_u32 s79, 0x100
	s_cbranch_scc1 .Lwo_half_skip_a

.Lwo_half_skip_a:
	s_setprio 0
	s_barrier
	s_add_i32 s8, 0, 0x18000
	s_add_i32 s9, 0, 0x1c000
	v_add_u32_e32 v148, s8, v237
	v_add_u32_e32 v164, s9, v237
	ds_read_b128 v[64:67], v148
	ds_read_b128 v[68:71], v148 offset:1024
	ds_read_b128 v[144:147], v148 offset:2048
	ds_read_b128 v[148:151], v148 offset:3072
	ds_read_b128 v[152:155], v164
	ds_read_b128 v[156:159], v164 offset:1024
	ds_read_b128 v[160:163], v164 offset:2048
	ds_read_b128 v[164:167], v164 offset:3072
	v_lshl_add_u64 v[240:241], v[240:241], 0, s[16:17]
	s_mov_b32 m0, s71
	v_lshl_add_u64 v[252:253], v[240:241], 0, v[190:191]
	ds_read_b128 v[168:171], v238 offset:32768
	ds_read_b128 v[172:175], v238 offset:33792
	ds_read_b128 v[176:179], v238 offset:34816
	ds_read_b128 v[180:183], v238 offset:35840
	ds_read_b128 v[218:221], v238 offset:36864
	ds_read_b128 v[222:225], v238 offset:37888
	ds_read_b128 v[226:229], v238 offset:38912
	ds_read_b128 v[230:233], v238 offset:39936
	s_mov_b32 m0, s69
	s_nop 0
	global_load_lds_dwordx4 v[248:249], off
	s_mov_b32 m0, s70
	s_nop 0
	global_load_lds_dwordx4 v[250:251], off
	s_mov_b32 m0, s71
	s_nop 0
	global_load_lds_dwordx4 v[252:253], off
	v_lshl_add_u64 v[240:241], v[240:241], 0, v[194:195]
	s_mov_b32 m0, s72
	s_nop 0
	global_load_lds_dwordx4 v[240:241], off
	s_waitcnt vmcnt(8)
	s_waitcnt lgkmcnt(0)
	s_barrier
	s_setprio 1
	s_waitcnt lgkmcnt(0)
	v_mfma_f32_16x16x32_bf16 v[140:143], v[64:67], v[168:171], v[140:143]
	v_mfma_f32_16x16x32_bf16 v[136:139], v[144:147], v[168:171], v[136:139]
	v_mfma_f32_16x16x32_bf16 v[124:127], v[64:67], v[176:179], v[124:127]
	v_mfma_f32_16x16x32_bf16 v[120:123], v[144:147], v[176:179], v[120:123]
	v_mfma_f32_16x16x32_bf16 v[108:111], v[64:67], v[218:221], v[108:111]
	v_mfma_f32_16x16x32_bf16 v[104:107], v[144:147], v[218:221], v[104:107]
	v_mfma_f32_16x16x32_bf16 v[92:95], v[64:67], v[226:229], v[92:95]
	v_mfma_f32_16x16x32_bf16 v[88:91], v[144:147], v[226:229], v[88:91]
	v_mfma_f32_16x16x32_bf16 v[140:143], v[68:71], v[172:175], v[140:143]
	v_mfma_f32_16x16x32_bf16 v[136:139], v[148:151], v[172:175], v[136:139]
	v_mfma_f32_16x16x32_bf16 v[124:127], v[68:71], v[180:183], v[124:127]
	v_mfma_f32_16x16x32_bf16 v[120:123], v[148:151], v[180:183], v[120:123]
	v_mfma_f32_16x16x32_bf16 v[108:111], v[68:71], v[222:225], v[108:111]
	v_mfma_f32_16x16x32_bf16 v[104:107], v[148:151], v[222:225], v[104:107]
	v_mfma_f32_16x16x32_bf16 v[92:95], v[68:71], v[230:233], v[92:95]
	v_mfma_f32_16x16x32_bf16 v[88:91], v[148:151], v[230:233], v[88:91]
	s_setprio 0
	s_setprio 1
	v_mfma_f32_16x16x32_bf16 v[132:135], v[152:155], v[168:171], v[132:135]
	v_mfma_f32_16x16x32_bf16 v[128:131], v[160:163], v[168:171], v[128:131]
	v_mfma_f32_16x16x32_bf16 v[116:119], v[152:155], v[176:179], v[116:119]
	v_mfma_f32_16x16x32_bf16 v[112:115], v[160:163], v[176:179], v[112:115]
	v_mfma_f32_16x16x32_bf16 v[100:103], v[152:155], v[218:221], v[100:103]
	v_mfma_f32_16x16x32_bf16 v[96:99], v[160:163], v[218:221], v[96:99]
	v_mfma_f32_16x16x32_bf16 v[84:87], v[152:155], v[226:229], v[84:87]
	v_mfma_f32_16x16x32_bf16 v[80:83], v[160:163], v[226:229], v[80:83]
	v_mfma_f32_16x16x32_bf16 v[132:135], v[156:159], v[172:175], v[132:135]
	v_mfma_f32_16x16x32_bf16 v[128:131], v[164:167], v[172:175], v[128:131]
	v_mfma_f32_16x16x32_bf16 v[116:119], v[156:159], v[180:183], v[116:119]
	v_mfma_f32_16x16x32_bf16 v[112:115], v[164:167], v[180:183], v[112:115]
	v_mfma_f32_16x16x32_bf16 v[100:103], v[156:159], v[222:225], v[100:103]
	v_mfma_f32_16x16x32_bf16 v[96:99], v[164:167], v[222:225], v[96:99]
	v_mfma_f32_16x16x32_bf16 v[84:87], v[156:159], v[230:233], v[84:87]
	v_mfma_f32_16x16x32_bf16 v[80:83], v[164:167], v[230:233], v[80:83]
	s_setprio 0
	s_barrier
	s_add_i32 s8, s8, s68
	v_lshl_add_u64 v[240:241], v[244:245], 0, s[26:27]
	s_mov_b32 m0, s8
	ds_read_b128 v[168:171], v238 offset:49152
	ds_read_b128 v[172:175], v238 offset:50176
	ds_read_b128 v[176:179], v238 offset:51200
	ds_read_b128 v[180:183], v238 offset:52224
	ds_read_b128 v[218:221], v238 offset:53248
	ds_read_b128 v[222:225], v238 offset:54272
	ds_read_b128 v[226:229], v238 offset:55296
	ds_read_b128 v[230:233], v238 offset:56320
	global_load_lds_dwordx4 v[240:241], off
	v_lshl_add_u64 v[240:241], v[246:247], 0, s[26:27]
	s_add_i32 m0, s8, 0x2000
	s_add_i32 s8, s9, s68
	global_load_lds_dwordx4 v[240:241], off
	v_lshl_add_u64 v[240:241], v[242:243], 0, s[28:29]
	v_lshl_add_u64 v[242:243], v[240:241], 0, v[192:193]
	s_mov_b32 m0, s8
	v_lshl_add_u64 v[240:241], v[240:241], 0, v[196:197]
	global_load_lds_dwordx4 v[242:243], off
	s_add_i32 m0, s8, 0x2000
	s_nop 0
	global_load_lds_dwordx4 v[240:241], off
	v_lshl_add_u64 v[240:241], v[248:249], 0, s[26:27]
	s_mov_b32 m0, s73
	s_nop 0
	global_load_lds_dwordx4 v[240:241], off
	v_lshl_add_u64 v[240:241], v[250:251], 0, s[26:27]
	s_mov_b32 m0, s74
	s_nop 0
	global_load_lds_dwordx4 v[240:241], off
	s_waitcnt vmcnt(8)
	s_waitcnt lgkmcnt(0)
	s_barrier
	s_setprio 1
	s_waitcnt lgkmcnt(0)
	s_bfe_u32 s101, s2, 0x10003
	s_sub_i32 s101, 2, s101
	s_cmp_eq_u32 s84, s101
	s_cbranch_scc0 .Lwo_half_full_b
	s_cmp_eq_u32 s79, 0x100
	s_cbranch_scc1 .Lwo_half_skip_b

.LBB0_961:
	v_lshlrev_b32_e32 v218, 5, v236
	s_lshl_b32 s7, s66, 10
	s_lshl_b32 s8, s77, 2
	s_add_i32 s7, s7, s8
	v_lshlrev_b32_e32 v219, 12, v235
	v_add_u32_e32 v218, s7, v218
	v_lshlrev_b32_e32 v222, 6, v235
	v_lshl_add_u32 v222, v236, 10, v222
	v_add_u32_e32 v219, v219, v218
	s_lshl_b32 s24, s6, 8
	s_add_i32 s24, s24, s76
	s_bfe_u32 s101, s2, 0x10003
	s_sub_i32 s101, 2, s101
	s_cmp_eq_u32 s84, s101
	s_cbranch_scc0 .Lepo_full_rows
	s_cmp_eq_u32 s79, 0x100
	s_cbranch_scc0 .Lepo_full_rows
	s_and_b32 s8, s2, 1
	s_lshl_b32 s8, s8, 7
	s_add_i32 s24, s24, s8
.Lepo_full_rows:
	s_lshl_b32 s10, s24, 12
	s_add_u32 s10, s20, s10
	s_addc_u32 s11, s21, 0
	s_lshl_b32 s98, s24, 11
	s_add_i32 s98, s98, 0x2800000
	s_add_u32 s98, s58, s98
	s_addc_u32 s99, s59, 0
	v_lshrrev_b32_e32 v220, 1, v219
	s_bfe_u32 s101, s2, 0x10003
	s_sub_i32 s101, 2, s101
	s_cmp_eq_u32 s84, s101
	s_cbranch_scc0 .Lepo_not_half
	s_cmp_eq_u32 s79, 0x100
	s_cbranch_scc1 .Lepo_half
